# layer-0 norm1 row loop: loop-top full drain replaced by vmcnt(8) (8 stores may stay in flight), drain moved to loop entry
# baseline (speedup 1.0000x reference)
; __device__ __forceinline__ void norm_rows(const Ctx& F, CParams& P, int layer, int which  , int t_first, int t_end, int t_stride) {
;     ...
;     f32x4 g[8];
; #pragma unroll
;     for (int j = 0; j < 8; ++j) g[j] = *(const f32x4*)(gn + j * 256 + lane * 4);
;     auto srcrow = [&](int t) { return from_in ? (t < TL ? P.x + (size_t)t * DM : P.ctx + (size_t)(t - TL) * DM) : X + (size_t)t * DM; };
;     f32x4 vn[8];
;     { const float* src = srcrow(t_first);
; #pragma unroll
;       for (int j = 0; j < 8; ++j) vn[j] = *(const f32x4*)(src + j * 256 + lane * 4); }
;     for (int t = t_first; t < t_end; t += t_stride) {
;         const int vs = vsel_of_row(t);
;         const float* shf = mod + (size_t)vs * 12288 + (which ? 3 : 0) * DM; const float* scl = shf + DM;
;         f32x4 v[8], sc[8], sh[8]; float ss = 0.f;
; #pragma unroll
;         for (int j = 0; j < 8; ++j) { v[j] = vn[j]; sc[j] = *(const f32x4*)(scl + j * 256 + lane * 4); sh[j] = *(const f32x4*)(shf + j * 256 + lane * 4); }
;         { const int tn = t + t_stride; const float* src = srcrow(tn < t_end ? tn : t);
; #pragma unroll
;           for (int j = 0; j < 8; ++j) vn[j] = *(const f32x4*)(src + j * 256 + lane * 4); }
; #pragma unroll
;         for (int j = 0; j < 8; ++j) ss += v[j][0] * v[j][0] + v[j][1] * v[j][1] + v[j][2] * v[j][2] + v[j][3] * v[j][3];
;         ss = wave_sum(ss);
;         const float rstd = rsqrtf(ss * (1.f / DM) + EPS);
.LBB0_1033:
	v_lshl_add_u64 v[34:35], v[94:95], 2, s[8:9]
	v_add_co_u32_e32 v36, vcc, 0x1000, v34
	s_nop 1
	v_addc_co_u32_e32 v37, vcc, 0, v35, vcc
	global_load_dwordx4 v[90:93], v[36:37], off offset:3072
	global_load_dwordx4 v[42:45], v[36:37], off offset:2048
	global_load_dwordx4 v[46:49], v[36:37], off offset:1024
	global_load_dwordx4 v[78:81], v[36:37], off
	global_load_dwordx4 v[74:77], v[34:35], off offset:3072
	global_load_dwordx4 v[70:73], v[34:35], off offset:2048
	global_load_dwordx4 v[66:69], v[34:35], off offset:1024
	global_load_dwordx4 v[62:65], v[34:35], off
	s_load_dwordx2 s[8:9], s[6:7], 0xe8
	s_lshl_b32 s6, s15, 3
	s_waitcnt lgkmcnt(0)
	s_add_u32 s10, s8, 0x100000
	s_addc_u32 s11, s9, 0
	s_lshl_b64 s[16:17], s[2:3], 12
	s_add_u32 s8, s8, s16
	s_addc_u32 s9, s9, s17
	v_lshl_add_u64 v[34:35], v[94:95], 1, s[8:9]
	s_mov_b64 s[8:9], 0x20c9c100
	s_ashr_i32 s7, s6, 31
	v_lshl_add_u64 v[96:97], v[34:35], 0, s[8:9]
	s_lshl_b64 s[8:9], s[6:7], 12
	s_waitcnt vmcnt(0)
.LBB0_1034:
	s_cmpk_lt_u32 s2, 0x4000
	s_waitcnt vmcnt(8)
	v_mul_f32_e32 v32, v63, v63
	v_mul_f32_e32 v34, v67, v67
	s_cselect_b32 s3, s95, 0x6000
	s_cmpk_gt_i32 s2, 0x1fff
	v_mul_f32_e32 v35, v71, v71
	v_fmac_f32_e32 v32, v62, v62
	v_fmac_f32_e32 v34, v66, v66
	s_cselect_b32 s3, s3, 0
	v_mul_f32_e32 v36, v75, v75
	v_fmac_f32_e32 v35, v70, v70
	v_fmac_f32_e32 v32, v64, v64
	v_fmac_f32_e32 v34, v68, v68
	s_lshl_b32 s3, s3, 2
	v_fmac_f32_e32 v36, v74, v74
	v_fmac_f32_e32 v35, v72, v72
	v_fmac_f32_e32 v32, v65, v65
	v_fmac_f32_e32 v34, v69, v69
	s_add_u32 s16, s10, s3
	v_lshlrev_b64 v[82:83], 2, v[94:95]
	v_fmac_f32_e32 v36, v76, v76
	v_fmac_f32_e32 v35, v73, v73
	v_add_f32_e32 v32, v32, v34
	s_addc_u32 s17, s11, 0
	v_fmac_f32_e32 v36, v77, v77
	v_add_f32_e32 v32, v32, v35
	v_lshl_add_u64 v[50:51], s[16:17], 0, v[82:83]
	v_mul_f32_e32 v40, v79, v79
	v_add_f32_e32 v32, v32, v36
	global_load_dwordx4 v[84:87], v[50:51], off
	global_load_dwordx4 v[34:37], v[50:51], off offset:1024
	v_fmac_f32_e32 v40, v78, v78
	v_add_co_u32_e32 v52, vcc, s95, v50
	v_fmac_f32_e32 v40, v80, v80
	s_nop 0
	v_addc_co_u32_e32 v53, vcc, 0, v51, vcc
	v_fmac_f32_e32 v40, v81, v81
	v_lshl_add_u64 v[38:39], v[50:51], 0, s[42:43]
	v_add_co_u32_e32 v58, vcc, s81, v50
	v_add_f32_e32 v32, v32, v40
	s_nop 0
	v_addc_co_u32_e32 v59, vcc, 0, v51, vcc
	global_load_dwordx4 v[106:109], v[38:39], off offset:1024
	global_load_dwordx4 v[110:113], v[38:39], off offset:2048
	global_load_dwordx4 v[114:117], v[52:53], off offset:-4096
	global_load_dwordx4 v[124:127], v[52:53], off
	global_load_dwordx4 v[128:131], v[38:39], off offset:3072
	s_nop 0
	global_load_dwordx4 v[38:41], v[58:59], off
	global_load_dwordx4 v[132:135], v[52:53], off offset:1024
	global_load_dwordx4 v[136:139], v[52:53], off offset:2048
	global_load_dwordx4 v[140:143], v[52:53], off offset:3072
	v_mul_f32_e32 v54, v47, v47
	v_mul_f32_e32 v55, v43, v43
	v_fmac_f32_e32 v54, v46, v46
	v_mul_f32_e32 v56, v91, v91
	v_fmac_f32_e32 v55, v42, v42
	v_fmac_f32_e32 v54, v48, v48
	v_fmac_f32_e32 v56, v90, v90
	v_fmac_f32_e32 v55, v44, v44
	v_fmac_f32_e32 v54, v49, v49
	v_fmac_f32_e32 v56, v92, v92
	v_fmac_f32_e32 v55, v45, v45
	v_add_f32_e32 v32, v32, v54
	v_fmac_f32_e32 v56, v93, v93
	v_add_f32_e32 v32, v32, v55
	v_add_f32_e32 v32, v32, v56
	ds_swizzle_b32 v52, v32 offset:swizzle(SWAP,16)
	s_add_i32 s7, s2, s6
	s_cmpk_lt_i32 s7, 0x4200
	s_cselect_b64 s[16:17], -1, 0
	s_waitcnt lgkmcnt(0)
	v_add_f32_e32 v32, v32, v52
	ds_swizzle_b32 v52, v32 offset:swizzle(SWAP,8)
	s_waitcnt lgkmcnt(0)
	v_add_f32_e32 v32, v32, v52
	ds_swizzle_b32 v52, v32 offset:swizzle(SWAP,4)
	s_waitcnt lgkmcnt(0)
	v_add_f32_e32 v32, v32, v52
	ds_swizzle_b32 v52, v32 offset:swizzle(SWAP,2)
	s_waitcnt lgkmcnt(0)
	v_add_f32_e32 v32, v32, v52
	ds_swizzle_b32 v52, v32 offset:swizzle(SWAP,1)
	s_waitcnt lgkmcnt(0)
	v_add_f32_e32 v32, v32, v52
	v_mov_b32_e32 v52, v32
	s_nop 1
	v_permlane32_swap_b32_e32 v32, v52
	v_add_f32_e32 v32, v32, v52
	v_fmamk_f32 v32, v32, 0x3a000000, v234
	v_mul_f32_e32 v52, 0x4b800000, v32
	v_cmp_gt_f32_e32 vcc, s57, v32
	s_waitcnt vmcnt(8)
	v_add_f32_e32 v144, 1.0, v106
	v_cndmask_b32_e32 v32, v32, v52, vcc
	v_rsq_f32_e32 v32, v32
	s_waitcnt vmcnt(6)
; __device__ __forceinline__ unsigned cvt_pk_bf16(float lo, float hi) { unsigned r; asm("v_cvt_pk_bf16_f32 %0, %1, %2" : "=v"(r) : "v"(lo), "v"(hi)); return r; }
; __device__ __forceinline__ void norm_rows(const Ctx& F, CParams& P, int layer, int which  , int t_first, int t_end, int t_stride) {
;     ...
;     for (int t = t_first; t < t_end; t += t_stride) {
;         const int vs = vsel_of_row(t);
;         const float* shf = mod + (size_t)vs * 12288 + (which ? 3 : 0) * DM; const float* scl = shf + DM;
;         f32x4 v[8], sc[8], sh[8]; float ss = 0.f;
; #pragma unroll
;         for (int j = 0; j < 8; ++j) { v[j] = vn[j]; sc[j] = *(const f32x4*)(scl + j * 256 + lane * 4); sh[j] = *(const f32x4*)(shf + j * 256 + lane * 4); }
;         { const int tn = t + t_stride; const float* src = srcrow(tn < t_end ? tn : t);
; #pragma unroll
;           for (int j = 0; j < 8; ++j) vn[j] = *(const f32x4*)(src + j * 256 + lane * 4); }
; #pragma unroll
;         for (int j = 0; j < 8; ++j) ss += v[j][0] * v[j][0] + v[j][1] * v[j][1] + v[j][2] * v[j][2] + v[j][3] * v[j][3];
;         ss = wave_sum(ss);
;         const float rstd = rsqrtf(ss * (1.f / DM) + EPS);
; #pragma unroll
;         for (int j = 0; j < 8; ++j) { const int c = j * 256 + lane * 4;
;             f32x4 y;
; #pragma unroll
;             for (int e = 0; e < 4; ++e) y[e] = (v[j][e] * rstd * g[j][e]) * (1.f + sc[j][e]) + sh[j][e];
;             u32x2 w; w.x = cvt_pk_bf16(y[0], y[1]); w.y = cvt_pk_bf16(y[2], y[3]);
;             *(u32x2*)(H + (size_t)t * DM + c) = w; }
	v_add_f32_e32 v101, 1.0, v115
	v_add_f32_e32 v102, 1.0, v116
	v_add_f32_e32 v123, 1.0, v117
	v_mul_f32_e32 v52, 0x45800000, v32
	v_cndmask_b32_e32 v32, v32, v52, vcc
	v_mul_f32_e32 v52, v62, v32
	v_mul_f32_e32 v53, v63, v32
	v_mul_f32_e32 v57, v64, v32
	v_mul_f32_e32 v100, v65, v32
	v_mul_f32_e32 v54, v66, v32
	v_mul_f32_e32 v55, v67, v32
	v_mul_f32_e32 v64, v73, v32
	v_mul_f32_e32 v66, v74, v32
	v_mul_f32_e32 v67, v75, v32
	v_mul_f32_e32 v73, v80, v32
	v_mul_f32_e32 v74, v46, v32
	v_mul_f32_e32 v75, v47, v32
	v_mul_f32_e32 v80, v42, v32
	v_mul_f32_e32 v89, v43, v32
	v_mul_f32_e32 v103, v44, v32
	v_mul_f32_e32 v104, v45, v32
	v_add_f32_e32 v46, 1.0, v114
	global_load_dwordx4 v[42:45], v[50:51], off offset:2048
	v_mul_f32_e32 v47, v0, v52
	v_mul_f32_e32 v62, v71, v32
	v_mul_f32_e32 v63, v72, v32
	v_mul_f32_e32 v71, v78, v32
	v_mul_f32_e32 v72, v79, v32
	v_mul_f32_e32 v78, v48, v32
	v_mul_f32_e32 v79, v49, v32
	v_fma_f32 v99, v46, v47, v84
	global_load_dwordx4 v[46:49], v[50:51], off offset:3072
	v_mul_f32_e32 v50, v1, v53
	v_mul_f32_e32 v51, v2, v57
	v_mul_f32_e32 v52, v3, v100
	v_mul_f32_e32 v56, v69, v32
	v_fma_f32 v100, v101, v50, v85
	v_fma_f32 v86, v102, v51, v86
	v_fmac_f32_e32 v87, v123, v52
	global_load_dwordx4 v[50:53], v[58:59], off offset:1024
	v_add_f32_e32 v145, 1.0, v107
	v_add_f32_e32 v146, 1.0, v109
	v_mul_f32_e32 v54, v4, v54
	v_mul_f32_e32 v55, v5, v55
	v_mul_f32_e32 v56, v7, v56
	v_mul_f32_e32 v60, v68, v32
	v_mul_f32_e32 v61, v70, v32
	v_fma_f32 v101, v144, v54, v34
	v_fma_f32 v102, v145, v55, v35
	v_fmac_f32_e32 v37, v146, v56
	global_load_dwordx4 v[54:57], v[58:59], off offset:2048
	v_mul_f32_e32 v34, v6, v60
	v_mul_f32_e32 v35, v8, v61
	global_load_dwordx4 v[58:61], v[58:59], off offset:3072
	s_and_b64 vcc, s[16:17], exec
	s_cselect_b32 s2, s7, s2
	s_add_i32 s15, s2, 0xffffc000
	s_ashr_i32 s3, s2, 31
	s_cmpk_lt_i32 s2, 0x4000
	s_cselect_b32 s3, s3, 0
	s_cselect_b32 s2, s2, s15
	s_cselect_b32 s15, s5, s1
	s_cselect_b32 s16, s4, s0
	s_lshl_b64 s[2:3], s[2:3], 13
	s_add_u32 s2, s16, s2
	v_mul_f32_e32 v70, v76, v32
	v_mul_f32_e32 v76, v81, v32
	v_add_f32_e32 v121, 1.0, v108
	v_add_f32_e32 v122, 1.0, v110
	s_addc_u32 s3, s15, s3
	v_mul_f32_e32 v68, v77, v32
	v_add_f32_e32 v119, 1.0, v112
	s_waitcnt vmcnt(10)
	v_add_f32_e32 v112, 1.0, v127
	v_fma_f32 v36, v121, v34, v36
	v_mul_f32_e32 v76, v19, v76
	v_add_f32_e32 v65, 1.0, v111
	v_add_f32_e32 v120, 1.0, v113
	s_waitcnt vmcnt(9)
	v_add_f32_e32 v69, 1.0, v128
	v_add_f32_e32 v117, 1.0, v129
	v_add_f32_e32 v113, 1.0, v130
	v_add_f32_e32 v118, 1.0, v131
	v_add_f32_e32 v114, 1.0, v124
	v_add_f32_e32 v115, 1.0, v125
	v_add_f32_e32 v116, 1.0, v126
	s_waitcnt vmcnt(7)
	v_add_f32_e32 v77, 1.0, v132
	v_add_f32_e32 v111, 1.0, v133
	v_mul_f32_e32 v62, v9, v62
	v_mul_f32_e32 v63, v10, v63
	v_mul_f32_e32 v64, v11, v64
	v_mul_f32_e32 v66, v12, v66
	v_mul_f32_e32 v67, v13, v67
	v_mul_f32_e32 v68, v15, v68
	v_mul_f32_e32 v70, v14, v70
	v_mul_f32_e32 v71, v16, v71
	v_mul_f32_e32 v72, v17, v72
	v_mul_f32_e32 v73, v18, v73
	v_fmac_f32_e32 v41, v112, v76
	v_mul_f32_e32 v74, v20, v74
	v_mul_f32_e32 v75, v21, v75
	v_add_f32_e32 v81, 1.0, v134
	v_add_f32_e32 v109, 1.0, v135
	v_fma_f32 v38, v114, v71, v38
	s_waitcnt vmcnt(4)
	v_fma_f32 v42, v122, v35, v42
	v_lshl_add_u64 v[34:35], s[2:3], 0, v[82:83]
	v_add_co_u32_e64 v112, s[2:3], s81, v34
	v_fma_f32 v43, v65, v62, v43
	v_fma_f32 v44, v119, v63, v44
	v_fmac_f32_e32 v45, v120, v64
	global_load_dwordx4 v[62:65], v[34:35], off
	v_fma_f32 v39, v115, v72, v39
	s_waitcnt vmcnt(4)
	v_fma_f32 v46, v69, v66, v46
	v_fma_f32 v47, v117, v67, v47
	v_fmac_f32_e32 v49, v118, v68
	global_load_dwordx4 v[66:69], v[34:35], off offset:1024
	v_fma_f32 v48, v113, v70, v48
	v_fma_f32 v40, v116, v73, v40
	global_load_dwordx4 v[70:73], v[34:35], off offset:2048
	v_addc_co_u32_e64 v113, s[2:3], 0, v35, s[2:3]
	s_waitcnt vmcnt(5)
	v_fma_f32 v50, v77, v74, v50
	v_fma_f32 v51, v111, v75, v51
	global_load_dwordx4 v[74:77], v[34:35], off offset:3072
	v_mul_f32_e32 v34, v22, v78
	v_mul_f32_e32 v35, v23, v79
	v_mul_f32_e32 v88, v90, v32
	v_add_f32_e32 v110, 1.0, v136
	v_add_f32_e32 v106, 1.0, v137
	v_add_f32_e32 v107, 1.0, v138
	v_add_f32_e32 v108, 1.0, v139
	v_mul_f32_e32 v78, v24, v80
	v_fma_f32 v52, v81, v34, v52
	v_fmac_f32_e32 v53, v109, v35
	v_mul_f32_e32 v34, v25, v89
	v_mul_f32_e32 v35, v26, v103
	v_mul_f32_e32 v82, v27, v104
	v_mul_f32_e32 v90, v91, v32
	v_mul_f32_e32 v91, v92, v32
	v_add_f32_e32 v105, 1.0, v140
	s_waitcnt vmcnt(5)
	v_fma_f32 v54, v110, v78, v54
	global_load_dwordx4 v[78:81], v[112:113], off
	v_fma_f32 v55, v106, v34, v55
	v_fma_f32 v56, v107, v35, v56
	v_fmac_f32_e32 v57, v108, v82
	global_load_dwordx4 v[82:85], v[112:113], off offset:1024
	v_mul_f32_e32 v34, v28, v88
	v_cvt_pk_bf16_f32 v35, v86, v87
	global_load_dwordx4 v[86:89], v[112:113], off offset:2048
	v_mul_f32_e32 v98, v93, v32
	v_add_f32_e32 v92, 1.0, v141
	v_add_f32_e32 v93, 1.0, v142
	s_waitcnt vmcnt(7)
	v_fma_f32 v58, v105, v34, v58
	v_mul_f32_e32 v34, v29, v90
	v_mul_f32_e32 v90, v30, v91
	v_fma_f32 v59, v92, v34, v59
	v_fma_f32 v60, v93, v90, v60
	global_load_dwordx4 v[90:93], v[112:113], off offset:3072
	v_add_f32_e32 v32, 1.0, v143
	v_mul_f32_e32 v34, v31, v98
	v_fmac_f32_e32 v61, v32, v34
	v_cvt_pk_bf16_f32 v34, v99, v100
	v_cvt_pk_bf16_f32 v99, v36, v37
	v_cvt_pk_bf16_f32 v36, v42, v43
	v_cvt_pk_bf16_f32 v37, v44, v45
	v_cvt_pk_bf16_f32 v42, v46, v47
	v_cvt_pk_bf16_f32 v43, v48, v49
	v_cvt_pk_bf16_f32 v44, v54, v55
	v_cvt_pk_bf16_f32 v45, v56, v57
	v_cvt_pk_bf16_f32 v46, v58, v59
	v_cvt_pk_bf16_f32 v47, v60, v61
	v_cvt_pk_bf16_f32 v98, v101, v102
	v_cvt_pk_bf16_f32 v38, v38, v39
	v_cvt_pk_bf16_f32 v39, v40, v41
	v_cvt_pk_bf16_f32 v40, v50, v51
	v_cvt_pk_bf16_f32 v41, v52, v53
	global_store_dwordx2 v[96:97], v[34:35], off
	global_store_dwordx2 v[96:97], v[98:99], off offset:512
	global_store_dwordx2 v[96:97], v[36:37], off offset:1024
	global_store_dwordx2 v[96:97], v[42:43], off offset:1536
	global_store_dwordx2 v[96:97], v[38:39], off offset:2048
	global_store_dwordx2 v[96:97], v[40:41], off offset:2560
	global_store_dwordx2 v[96:97], v[44:45], off offset:3072
	global_store_dwordx2 v[96:97], v[46:47], off offset:3584
	s_mov_b32 s2, s7
	v_lshl_add_u64 v[96:97], v[96:97], 0, s[8:9]
	s_waitcnt vmcnt(10)
	v_mov_b64_e32 v[46:47], v[82:83]
	v_mov_b64_e32 v[48:49], v[84:85]
	s_waitcnt vmcnt(9)
	v_mov_b64_e32 v[42:43], v[86:87]
	v_mov_b64_e32 v[44:45], v[88:89]
	s_cbranch_vccnz .LBB0_1034
